# v28 + ctx 64x64 tile GEMM of the attention out-projection phase: all 8 k-step global loads issued up front with counted waits
# speedup vs baseline: 1.0001x; 1.0001x over previous
; #define LAS __attribute__((address_space(3)))
; template <class Epi>
; __device__ __forceinline__ void gemm64_tile(LAS unsigned char* lds, const bf16_t* A, const bf16_t* Bt, const Epi& E) {
;     constexpr int K = 1024, BK = 128, PITCH = BK * 2 + 16, NKT = K / BK;
;     const int tid = threadIdx.x, lane = tid & 63, wave = __builtin_amdgcn_readfirstlane(tid >> 6), fr = lane & 15, fq = lane >> 4, wr = wave >> 1, wc = wave & 1;
;     LAS unsigned char* As = lds; LAS unsigned char* Bs = lds + 64 * PITCH;
;     const int srow = tid >> 4, sch = tid & 15;
;     const bf16_t* ga = A + (size_t)srow * K + sch * 8; const bf16_t* gb = Bt + (size_t)srow * K + sch * 8;
;     u32x4 ra[2], rb[2];
; #pragma unroll
;     for (int i = 0; i < 2; ++i) { ra[i] = *(const u32x4*)(ga + (size_t)(32 * i) * K); rb[i] = *(const u32x4*)(gb + (size_t)(32 * i) * K); }
;     f32x4 acc[2] = {(f32x4){0.f, 0.f, 0.f, 0.f}, (f32x4){0.f, 0.f, 0.f, 0.f}};
;     for (int kt = 0; kt < NKT; ++kt) {
;         __syncthreads();
; #pragma unroll
;         for (int i = 0; i < 2; ++i) { *(LAS u32x4*)(As + (srow + 32 * i) * PITCH + sch * 16) = ra[i]; *(LAS u32x4*)(Bs + (srow + 32 * i) * PITCH + sch * 16) = rb[i]; }
;         __syncthreads();
;         if (kt + 1 < NKT) {
; #pragma unroll
;             for (int i = 0; i < 2; ++i) { ra[i] = *(const u32x4*)(ga + (size_t)(32 * i) * K + (kt + 1) * BK); rb[i] = *(const u32x4*)(gb + (size_t)(32 * i) * K + (kt + 1) * BK); }
;         }
; #pragma unroll
;         for (int ks = 0; ks < 4; ++ks) {
;             const bf16x8 Af = *(const LAS bf16x8*)(As + (16 * wr + fr) * PITCH + (32 * ks + 8 * fq) * 2);
; #pragma unroll
;             for (int n = 0; n < 2; ++n) {
;                 const bf16x8 Bf = *(const LAS bf16x8*)(Bs + (32 * wc + 16 * n + fr) * PITCH + (32 * ks + 8 * fq) * 2);
;                 acc[n] = __builtin_amdgcn_mfma_f32_16x16x32_bf16(Bf, Af, acc[n], 0, 0, 0);
;             }
;         }
;     }
.LBB0_486:
	s_ashr_i32 s22, s12, 4
	s_ashr_i32 s23, s22, 31
	s_and_b32 s38, s12, 15
	s_lshl_b64 s[0:1], s[22:23], 18
	s_add_u32 s24, s40, s0
	s_addc_u32 s25, s41, s1
	s_lshl_b32 s4, s22, 6
	s_add_i32 s0, s4, 0x4000
	s_ashr_i32 s1, s0, 31
	s_lshl_b32 s5, s38, 6
	s_lshl_b64 s[36:37], s[0:1], 11
	s_add_u32 s36, s6, s36
	s_addc_u32 s37, s7, s37
	s_lshl_b32 s23, s38, 17
	v_lshlrev_b32_e32 v0, 11, v175
	v_mov_b32_e32 v1, 0
	s_add_u32 s38, s64, s23
	v_lshl_add_u64 v[2:3], s[36:37], 0, v[0:1]
	v_mov_b32_e32 v145, v1
	s_addc_u32 s39, s65, 0
	v_lshl_add_u64 v[2:3], v[2:3], 0, v[144:145]
	s_mov_b32 s23, 0x10000
	v_lshl_add_u64 v[4:5], s[38:39], 0, v[0:1]
	v_add_co_u32_e32 v6, vcc, s23, v2
	s_waitcnt vmcnt(0)
	s_barrier
	v_lshl_add_u64 v[8:9], v[4:5], 0, v[144:145]
	global_load_dwordx4 v[12:15], v[2:3], off
	global_load_dwordx4 v[16:19], v[8:9], off
	v_addc_co_u32_e32 v7, vcc, 0, v3, vcc
	global_load_dwordx4 v[20:23], v[6:7], off
	v_add_co_u32_e32 v10, vcc, s23, v8
	v_mul_u32_u24_e32 v0, 0x110, v175
	s_nop 0
	v_addc_co_u32_e32 v11, vcc, 0, v9, vcc
	global_load_dwordx4 v[24:27], v[10:11], off
	global_load_dwordx4 v[100:103], v[2:3], off offset:256
	global_load_dwordx4 v[104:107], v[8:9], off offset:256
	global_load_dwordx4 v[108:111], v[6:7], off offset:256
	global_load_dwordx4 v[112:115], v[10:11], off offset:256
	global_load_dwordx4 v[116:119], v[8:9], off offset:512
	global_load_dwordx4 v[120:123], v[2:3], off offset:512
	global_load_dwordx4 v[124:127], v[6:7], off offset:512
	global_load_dwordx4 v[128:131], v[10:11], off offset:512
	global_load_dwordx4 v[132:135], v[8:9], off offset:768
	global_load_dwordx4 v[136:139], v[2:3], off offset:768
	global_load_dwordx4 v[140:143], v[6:7], off offset:768
	global_load_dwordx4 v[148:151], v[10:11], off offset:768
	global_load_dwordx4 v[152:155], v[8:9], off offset:1024
	global_load_dwordx4 v[156:159], v[2:3], off offset:1024
	global_load_dwordx4 v[160:163], v[6:7], off offset:1024
	global_load_dwordx4 v[164:167], v[10:11], off offset:1024
	global_load_dwordx4 v[168:171], v[8:9], off offset:1280
	global_load_dwordx4 v[176:179], v[2:3], off offset:1280
	global_load_dwordx4 v[180:183], v[6:7], off offset:1280
	global_load_dwordx4 v[184:187], v[10:11], off offset:1280
	global_load_dwordx4 v[188:191], v[8:9], off offset:1536
	global_load_dwordx4 v[196:199], v[2:3], off offset:1536
	global_load_dwordx4 v[200:203], v[6:7], off offset:1536
	global_load_dwordx4 v[204:207], v[10:11], off offset:1536
	global_load_dwordx4 v[208:211], v[8:9], off offset:1792
	global_load_dwordx4 v[212:215], v[2:3], off offset:1792
	global_load_dwordx4 v[216:219], v[6:7], off offset:1792
	global_load_dwordx4 v[220:223], v[10:11], off offset:1792
	v_add3_u32 v68, 0, v144, v0
	s_barrier
	v_readfirstlane_b32 s36, v192
	s_bfe_u32 s23, s36, 0x10006
	s_lshr_b32 s36, s36, 3
	s_and_b32 s38, s36, 0x1ffffff0
	s_lshl_b32 s36, s23, 5
	v_add_u32_e32 v4, 0, v174
	s_movk_i32 s37, 0x110
	v_or_b32_e32 v0, s36, v173
	v_mad_u32_u24 v69, v0, s37, v4
	v_or_b32_e32 v0, s38, v173
	v_mad_u64_u32 v[4:5], s[38:39], v0, s37, v[4:5]
	s_waitcnt vmcnt(31)
	ds_write_b128 v68, v[12:15]
	s_waitcnt vmcnt(29)
	ds_write_b128 v68, v[20:23] offset:8704
	ds_write_b128 v68, v[16:19] offset:17408
	s_waitcnt vmcnt(28)
	ds_write_b128 v68, v[24:27] offset:26112
	s_waitcnt lgkmcnt(0)
	s_barrier
	ds_read_b128 v[28:31], v69 offset:17408
	ds_read_b128 v[32:35], v4
	ds_read_b128 v[36:39], v4 offset:64
	ds_read_b128 v[40:43], v69 offset:17472
	ds_read_b128 v[44:47], v69 offset:21760
	ds_read_b128 v[48:51], v69 offset:21824
	s_waitcnt lgkmcnt(4)
	v_mfma_f32_16x16x32_bf16 v[28:31], v[28:31], v[32:35], 0
	s_waitcnt lgkmcnt(1)
	v_mfma_f32_16x16x32_bf16 v[32:35], v[44:47], v[32:35], 0
	ds_read_b128 v[44:47], v69 offset:17536
	ds_read_b128 v[52:55], v4 offset:128
	ds_read_b128 v[56:59], v4 offset:192
	v_mfma_f32_16x16x32_bf16 v[28:31], v[40:43], v[36:39], v[28:31]
	ds_read_b128 v[40:43], v69 offset:17600
	ds_read_b128 v[60:63], v69 offset:21888
	ds_read_b128 v[64:67], v69 offset:21952
	s_waitcnt lgkmcnt(0)
	s_barrier
	v_mfma_f32_16x16x32_bf16 v[32:35], v[48:51], v[36:39], v[32:35]
	s_waitcnt vmcnt(27)
	ds_write_b128 v68, v[100:103]
	s_waitcnt vmcnt(26)
	ds_write_b128 v68, v[104:107] offset:17408
	s_waitcnt vmcnt(25)
	ds_write_b128 v68, v[108:111] offset:8704
	s_waitcnt vmcnt(24)
	ds_write_b128 v68, v[112:115] offset:26112
	s_waitcnt lgkmcnt(0)
	s_barrier
	v_mfma_f32_16x16x32_bf16 v[20:23], v[60:63], v[52:55], v[32:35]
	s_nop 1
	ds_read_b128 v[36:39], v69 offset:17408
	v_mfma_f32_16x16x32_bf16 v[28:31], v[44:47], v[52:55], v[28:31]
	v_mfma_f32_16x16x32_bf16 v[28:31], v[40:43], v[56:59], v[28:31]
	ds_read_b128 v[40:43], v4
	ds_read_b128 v[44:47], v4 offset:64
	ds_read_b128 v[48:51], v69 offset:17472
	v_mfma_f32_16x16x32_bf16 v[20:23], v[64:67], v[56:59], v[20:23]
	s_waitcnt lgkmcnt(2)
	v_mfma_f32_16x16x32_bf16 v[28:31], v[36:39], v[40:43], v[28:31]
	ds_read_b128 v[36:39], v69 offset:21760
	ds_read_b128 v[52:55], v69 offset:21824
	s_waitcnt lgkmcnt(1)
	v_mfma_f32_16x16x32_bf16 v[20:23], v[36:39], v[40:43], v[20:23]
	ds_read_b128 v[36:39], v69 offset:17536
	ds_read_b128 v[40:43], v4 offset:128
	ds_read_b128 v[56:59], v4 offset:192
	v_mfma_f32_16x16x32_bf16 v[28:31], v[48:51], v[44:47], v[28:31]
	ds_read_b128 v[48:51], v69 offset:17600
	ds_read_b128 v[60:63], v69 offset:21888
	ds_read_b128 v[64:67], v69 offset:21952
	s_waitcnt lgkmcnt(0)
	s_barrier
	v_mfma_f32_16x16x32_bf16 v[28:31], v[36:39], v[40:43], v[28:31]
	s_waitcnt vmcnt(22)
	ds_write_b128 v68, v[120:123]
	ds_write_b128 v68, v[116:119] offset:17408
	s_waitcnt vmcnt(21)
	ds_write_b128 v68, v[124:127] offset:8704
	s_waitcnt vmcnt(20)
	ds_write_b128 v68, v[128:131] offset:26112
	s_waitcnt lgkmcnt(0)
	s_barrier
; #define LAS __attribute__((address_space(3)))
; template <class Epi>
; __device__ __forceinline__ void gemm64_tile(LAS unsigned char* lds, const bf16_t* A, const bf16_t* Bt, const Epi& E) {
;     ...
;     for (int kt = 0; kt < NKT; ++kt) {
;         __syncthreads();
; #pragma unroll
;         for (int i = 0; i < 2; ++i) { *(LAS u32x4*)(As + (srow + 32 * i) * PITCH + sch * 16) = ra[i]; *(LAS u32x4*)(Bs + (srow + 32 * i) * PITCH + sch * 16) = rb[i]; }
;         __syncthreads();
;         if (kt + 1 < NKT) {
; #pragma unroll
;             for (int i = 0; i < 2; ++i) { ra[i] = *(const u32x4*)(ga + (size_t)(32 * i) * K + (kt + 1) * BK); rb[i] = *(const u32x4*)(gb + (size_t)(32 * i) * K + (kt + 1) * BK); }
;         }
; #pragma unroll
;         for (int ks = 0; ks < 4; ++ks) {
;             const bf16x8 Af = *(const LAS bf16x8*)(As + (16 * wr + fr) * PITCH + (32 * ks + 8 * fq) * 2);
; #pragma unroll
;             for (int n = 0; n < 2; ++n) {
;                 const bf16x8 Bf = *(const LAS bf16x8*)(Bs + (32 * wc + 16 * n + fr) * PITCH + (32 * ks + 8 * fq) * 2);
;                 acc[n] = __builtin_amdgcn_mfma_f32_16x16x32_bf16(Bf, Af, acc[n], 0, 0, 0);
;             }
;         }
;     }
	ds_read_b128 v[36:39], v69 offset:17408
	v_mfma_f32_16x16x32_bf16 v[20:23], v[52:55], v[44:47], v[20:23]
	v_mfma_f32_16x16x32_bf16 v[20:23], v[60:63], v[40:43], v[20:23]
	v_mfma_f32_16x16x32_bf16 v[28:31], v[48:51], v[56:59], v[28:31]
	ds_read_b128 v[40:43], v4
	ds_read_b128 v[44:47], v4 offset:64
	ds_read_b128 v[48:51], v69 offset:17472
	v_mfma_f32_16x16x32_bf16 v[20:23], v[64:67], v[56:59], v[20:23]
	s_waitcnt lgkmcnt(2)
	v_mfma_f32_16x16x32_bf16 v[28:31], v[36:39], v[40:43], v[28:31]
	ds_read_b128 v[36:39], v69 offset:21760
	ds_read_b128 v[52:55], v69 offset:21824
	s_waitcnt lgkmcnt(1)
	v_mfma_f32_16x16x32_bf16 v[20:23], v[36:39], v[40:43], v[20:23]
	ds_read_b128 v[36:39], v69 offset:17536
	ds_read_b128 v[40:43], v4 offset:128
	ds_read_b128 v[56:59], v4 offset:192
	v_mfma_f32_16x16x32_bf16 v[28:31], v[48:51], v[44:47], v[28:31]
	ds_read_b128 v[48:51], v69 offset:17600
	ds_read_b128 v[60:63], v69 offset:21888
	ds_read_b128 v[64:67], v69 offset:21952
	s_waitcnt lgkmcnt(0)
	s_barrier
	v_mfma_f32_16x16x32_bf16 v[28:31], v[36:39], v[40:43], v[28:31]
	s_waitcnt vmcnt(18)
	ds_write_b128 v68, v[136:139]
	ds_write_b128 v68, v[132:135] offset:17408
	s_waitcnt vmcnt(17)
	ds_write_b128 v68, v[140:143] offset:8704
	s_waitcnt vmcnt(16)
	ds_write_b128 v68, v[148:151] offset:26112
	s_waitcnt lgkmcnt(0)
	s_barrier
	ds_read_b128 v[36:39], v69 offset:17408
	v_mfma_f32_16x16x32_bf16 v[20:23], v[52:55], v[44:47], v[20:23]
	v_mfma_f32_16x16x32_bf16 v[20:23], v[60:63], v[40:43], v[20:23]
	v_mfma_f32_16x16x32_bf16 v[28:31], v[48:51], v[56:59], v[28:31]
	ds_read_b128 v[40:43], v4
	ds_read_b128 v[44:47], v4 offset:64
	ds_read_b128 v[48:51], v69 offset:17472
	v_mfma_f32_16x16x32_bf16 v[20:23], v[64:67], v[56:59], v[20:23]
	s_waitcnt lgkmcnt(2)
	v_mfma_f32_16x16x32_bf16 v[28:31], v[36:39], v[40:43], v[28:31]
	ds_read_b128 v[36:39], v69 offset:21760
	ds_read_b128 v[52:55], v69 offset:21824
	s_waitcnt lgkmcnt(1)
	v_mfma_f32_16x16x32_bf16 v[20:23], v[36:39], v[40:43], v[20:23]
	ds_read_b128 v[36:39], v69 offset:17536
	ds_read_b128 v[40:43], v4 offset:128
	ds_read_b128 v[56:59], v4 offset:192
	v_mfma_f32_16x16x32_bf16 v[28:31], v[48:51], v[44:47], v[28:31]
	ds_read_b128 v[48:51], v69 offset:17600
	ds_read_b128 v[60:63], v69 offset:21888
	ds_read_b128 v[64:67], v69 offset:21952
	s_waitcnt lgkmcnt(0)
	s_barrier
	v_mfma_f32_16x16x32_bf16 v[28:31], v[36:39], v[40:43], v[28:31]
	s_waitcnt vmcnt(14)
	ds_write_b128 v68, v[156:159]
	ds_write_b128 v68, v[152:155] offset:17408
	s_waitcnt vmcnt(13)
	ds_write_b128 v68, v[160:163] offset:8704
	s_waitcnt vmcnt(12)
	ds_write_b128 v68, v[164:167] offset:26112
	s_waitcnt lgkmcnt(0)
	s_barrier
	ds_read_b128 v[36:39], v69 offset:17408
	v_mfma_f32_16x16x32_bf16 v[20:23], v[52:55], v[44:47], v[20:23]
	v_mfma_f32_16x16x32_bf16 v[20:23], v[60:63], v[40:43], v[20:23]
	v_mfma_f32_16x16x32_bf16 v[28:31], v[48:51], v[56:59], v[28:31]
	ds_read_b128 v[40:43], v4
	ds_read_b128 v[44:47], v4 offset:64
	ds_read_b128 v[48:51], v69 offset:17472
	v_mfma_f32_16x16x32_bf16 v[20:23], v[64:67], v[56:59], v[20:23]
	s_waitcnt lgkmcnt(2)
	v_mfma_f32_16x16x32_bf16 v[28:31], v[36:39], v[40:43], v[28:31]
	ds_read_b128 v[36:39], v69 offset:21760
	ds_read_b128 v[52:55], v69 offset:21824
	s_waitcnt lgkmcnt(1)
	v_mfma_f32_16x16x32_bf16 v[20:23], v[36:39], v[40:43], v[20:23]
	ds_read_b128 v[36:39], v69 offset:17536
	ds_read_b128 v[40:43], v4 offset:128
	ds_read_b128 v[56:59], v4 offset:192
	v_mfma_f32_16x16x32_bf16 v[28:31], v[48:51], v[44:47], v[28:31]
	ds_read_b128 v[48:51], v69 offset:17600
	ds_read_b128 v[60:63], v69 offset:21888
	ds_read_b128 v[64:67], v69 offset:21952
	s_waitcnt lgkmcnt(0)
	s_barrier
	v_mfma_f32_16x16x32_bf16 v[28:31], v[36:39], v[40:43], v[28:31]
	s_waitcnt vmcnt(10)
	ds_write_b128 v68, v[176:179]
	ds_write_b128 v68, v[168:171] offset:17408
	s_waitcnt vmcnt(9)
	ds_write_b128 v68, v[180:183] offset:8704
	s_waitcnt vmcnt(8)
	ds_write_b128 v68, v[184:187] offset:26112
	s_waitcnt lgkmcnt(0)
	s_barrier
	ds_read_b128 v[36:39], v69 offset:17408
	v_mfma_f32_16x16x32_bf16 v[20:23], v[52:55], v[44:47], v[20:23]
	v_mfma_f32_16x16x32_bf16 v[20:23], v[60:63], v[40:43], v[20:23]
	v_mfma_f32_16x16x32_bf16 v[28:31], v[48:51], v[56:59], v[28:31]
	ds_read_b128 v[40:43], v4
	ds_read_b128 v[44:47], v4 offset:64
	ds_read_b128 v[48:51], v69 offset:17472
	v_mfma_f32_16x16x32_bf16 v[20:23], v[64:67], v[56:59], v[20:23]
	s_waitcnt lgkmcnt(2)
	v_mfma_f32_16x16x32_bf16 v[28:31], v[36:39], v[40:43], v[28:31]
	ds_read_b128 v[36:39], v69 offset:21760
	ds_read_b128 v[52:55], v69 offset:21824
	s_waitcnt lgkmcnt(1)
	v_mfma_f32_16x16x32_bf16 v[20:23], v[36:39], v[40:43], v[20:23]
	ds_read_b128 v[36:39], v69 offset:17536
	ds_read_b128 v[40:43], v4 offset:128
	ds_read_b128 v[56:59], v4 offset:192
	v_mfma_f32_16x16x32_bf16 v[28:31], v[48:51], v[44:47], v[28:31]
	ds_read_b128 v[48:51], v69 offset:17600
	ds_read_b128 v[60:63], v69 offset:21888
	ds_read_b128 v[64:67], v69 offset:21952
	s_waitcnt lgkmcnt(0)
	s_barrier
; #define LAS __attribute__((address_space(3)))
; template <class Epi>
; __device__ __forceinline__ void gemm64_tile(LAS unsigned char* lds, const bf16_t* A, const bf16_t* Bt, const Epi& E) {
;     ...
;     for (int kt = 0; kt < NKT; ++kt) {
;         __syncthreads();
; #pragma unroll
;         for (int i = 0; i < 2; ++i) { *(LAS u32x4*)(As + (srow + 32 * i) * PITCH + sch * 16) = ra[i]; *(LAS u32x4*)(Bs + (srow + 32 * i) * PITCH + sch * 16) = rb[i]; }
;         __syncthreads();
;         if (kt + 1 < NKT) {
; #pragma unroll
;             for (int i = 0; i < 2; ++i) { ra[i] = *(const u32x4*)(ga + (size_t)(32 * i) * K + (kt + 1) * BK); rb[i] = *(const u32x4*)(gb + (size_t)(32 * i) * K + (kt + 1) * BK); }
;         }
; #pragma unroll
;         for (int ks = 0; ks < 4; ++ks) {
;             const bf16x8 Af = *(const LAS bf16x8*)(As + (16 * wr + fr) * PITCH + (32 * ks + 8 * fq) * 2);
; #pragma unroll
;             for (int n = 0; n < 2; ++n) {
;                 const bf16x8 Bf = *(const LAS bf16x8*)(Bs + (32 * wc + 16 * n + fr) * PITCH + (32 * ks + 8 * fq) * 2);
;                 acc[n] = __builtin_amdgcn_mfma_f32_16x16x32_bf16(Bf, Af, acc[n], 0, 0, 0);
;             }
;         }
;     }
;     __syncthreads();
;     E(acc, wr, wc, fr, fq, lds);
; }
;     __device__ __forceinline__ void operator()(f32x4 (&acc)[2], int wr, int wc, int fr, int fq, LAS unsigned char* lds) const {
;         LAS float* P = (LAS float*)(lds + LDS_TOP + 64);
;         LAS float* S = P + 128;
;         const int tid = threadIdx.x, row = 16 * wr + fr;
;         f32x4 x[2]; float q = 0.f;
; #pragma unroll
;         for (int n = 0; n < 2; ++n) { const int c = col0 + 32 * wc + 16 * n + 4 * fq;
;             x[n] = *(const f32x4*)(base + (size_t)row * D + c) + *(const f32x4*)(modc + 2048 + c) * acc[n];
;             q += (x[n][0] * x[n][0] + x[n][1] * x[n][1]) + (x[n][2] * x[n][2] + x[n][3] * x[n][3]); }
;         q += __shfl_xor(q, 16); q += __shfl_xor(q, 32);
;         if (fq == 0) P[row * 2 + wc] = q;
	v_mfma_f32_16x16x32_bf16 v[28:31], v[36:39], v[40:43], v[28:31]
	s_waitcnt vmcnt(6)
	ds_write_b128 v68, v[196:199]
	ds_write_b128 v68, v[188:191] offset:17408
	s_waitcnt vmcnt(5)
	ds_write_b128 v68, v[200:203] offset:8704
	s_waitcnt vmcnt(4)
	ds_write_b128 v68, v[204:207] offset:26112
	s_waitcnt lgkmcnt(0)
	s_barrier
	ds_read_b128 v[10:13], v69 offset:17408
	v_mfma_f32_16x16x32_bf16 v[20:23], v[52:55], v[44:47], v[20:23]
	v_lshl_or_b32 v2, v172, 2, s36
	v_mov_b32_e32 v3, v1
	s_add_u32 s36, s30, 0xe000
	v_mfma_f32_16x16x32_bf16 v[6:9], v[48:51], v[56:59], v[28:31]
	s_addc_u32 s37, s31, 0
	v_mfma_f32_16x16x32_bf16 v[18:21], v[60:63], v[40:43], v[20:23]
	s_nop 0
	ds_read_b128 v[28:31], v4
	ds_read_b128 v[40:43], v4 offset:64
	ds_read_b128 v[44:47], v69 offset:17472
	ds_read_b128 v[48:51], v69 offset:21824
	s_waitcnt lgkmcnt(3)
	v_mfma_f32_16x16x32_bf16 v[6:9], v[10:13], v[28:31], v[6:9]
	ds_read_b128 v[10:13], v69 offset:21760
	v_mfma_f32_16x16x32_bf16 v[18:21], v[64:67], v[56:59], v[18:21]
	s_waitcnt lgkmcnt(0)
	v_mfma_f32_16x16x32_bf16 v[18:21], v[10:13], v[28:31], v[18:21]
	ds_read_b128 v[28:31], v69 offset:17536
	v_or_b32_e32 v12, s5, v2
	v_lshlrev_b64 v[10:11], 12, v[0:1]
	v_mfma_f32_16x16x32_bf16 v[6:9], v[44:47], v[40:43], v[6:9]
	ds_read_b128 v[44:47], v4 offset:128
	ds_read_b128 v[52:55], v69 offset:21888
	v_lshl_add_u64 v[10:11], s[24:25], 0, v[10:11]
	v_lshlrev_b32_e32 v2, 2, v12
	v_mfma_f32_16x16x32_bf16 v[18:21], v[48:51], v[40:43], v[18:21]
	ds_read_b128 v[40:43], v4 offset:192
	ds_read_b128 v[48:51], v69 offset:17600
	ds_read_b128 v[56:59], v69 offset:21952
	s_waitcnt lgkmcnt(0)
	s_barrier
	s_waitcnt vmcnt(2)
	ds_write_b128 v68, v[212:215]
	ds_write_b128 v68, v[208:211] offset:17408
	s_waitcnt vmcnt(1)
	ds_write_b128 v68, v[216:219] offset:8704
	s_waitcnt vmcnt(0)
	ds_write_b128 v68, v[220:223] offset:26112
	s_waitcnt lgkmcnt(0)
	s_barrier
	ds_read_b128 v[14:17], v69 offset:17408
	v_mfma_f32_16x16x32_bf16 v[6:9], v[28:31], v[44:47], v[6:9]
	ds_read_b128 v[22:25], v4
	ds_read_b128 v[26:29], v69 offset:21760
	ds_read_b128 v[30:33], v4 offset:64
	ds_read_b128 v[34:37], v69 offset:17472
	v_or_b32_e32 v5, 16, v12
	v_mfma_f32_16x16x32_bf16 v[18:21], v[52:55], v[44:47], v[18:21]
	v_mfma_f32_16x16x32_bf16 v[6:9], v[48:51], v[40:43], v[6:9]
	v_mfma_f32_16x16x32_bf16 v[18:21], v[56:59], v[40:43], v[18:21]
	v_lshl_add_u64 v[42:43], v[10:11], 0, v[2:3]
	v_lshlrev_b32_e32 v3, 2, v5
	s_waitcnt lgkmcnt(3)
	v_mfma_f32_16x16x32_bf16 v[6:9], v[14:17], v[22:25], v[6:9]
	ds_read_b128 v[14:17], v69 offset:21824
	s_waitcnt lgkmcnt(3)
	v_mfma_f32_16x16x32_bf16 v[18:21], v[26:29], v[22:25], v[18:21]
	ds_read_b128 v[22:25], v69 offset:17536
	s_waitcnt lgkmcnt(2)
	v_mfma_f32_16x16x32_bf16 v[6:9], v[34:37], v[30:33], v[6:9]
	ds_read_b128 v[26:29], v4 offset:128
	ds_read_b128 v[34:37], v69 offset:21888
	s_waitcnt lgkmcnt(3)
	v_mfma_f32_16x16x32_bf16 v[14:17], v[14:17], v[30:33], v[18:21]
	s_nop 2
	ds_read_b128 v[18:21], v4 offset:192
	ds_read_b128 v[30:33], v69 offset:17600
	ds_read_b128 v[38:41], v69 offset:21952
	s_waitcnt lgkmcnt(0)
	s_barrier
	v_mfma_f32_16x16x32_bf16 v[4:7], v[22:25], v[26:29], v[6:9]
	v_mfma_f32_16x16x32_bf16 v[8:11], v[34:37], v[26:29], v[14:17]
	s_nop 2
	global_load_dwordx4 v[14:17], v2, s[36:37]
	global_load_dwordx4 v[22:25], v[42:43], off
	global_load_dwordx4 v[26:29], v[42:43], off offset:64
	v_mfma_f32_16x16x32_bf16 v[4:7], v[30:33], v[18:21], v[4:7]
	global_load_dwordx4 v[30:33], v3, s[36:37]
	v_mfma_f32_16x16x32_bf16 v[18:21], v[38:41], v[18:21], v[8:11]
	s_waitcnt vmcnt(2)
	s_nop 4
	v_pk_fma_f32 v[8:9], v[6:7], v[16:17], v[24:25]
	v_pk_fma_f32 v[10:11], v[4:5], v[14:15], v[22:23]
	v_mul_f32_e32 v14, v9, v9
	v_mul_f32_e32 v13, v11, v11
	v_fmac_f32_e32 v13, v10, v10
	s_waitcnt vmcnt(0)
	v_pk_fma_f32 v[4:5], v[20:21], v[32:33], v[28:29]
	v_pk_fma_f32 v[6:7], v[18:19], v[30:31], v[26:27]
	v_mul_f32_e32 v16, v5, v5
	v_mul_f32_e32 v15, v7, v7
	v_fmac_f32_e32 v14, v8, v8
	v_fmac_f32_e32 v15, v6, v6
	v_fmac_f32_e32 v16, v4, v4
	v_add_f32_e32 v13, v13, v14
	v_add_f32_e32 v14, v15, v16
	v_add_f32_e32 v13, v13, v14
	ds_bpermute_b32 v14, v96, v13
	s_waitcnt lgkmcnt(0)
	v_add_f32_e32 v13, v13, v14
	ds_bpermute_b32 v14, v97, v13
	s_and_saveexec_b64 s[24:25], s[2:3]
	s_cbranch_execz .LBB0_488
	s_lshl_b32 s2, s23, 2
	s_add_i32 s2, s2, 0
	v_lshl_add_u32 v15, v0, 3, s2
	v_add_u32_e32 v15, 0x25040, v15
	s_waitcnt lgkmcnt(0)
	v_add_f32_e32 v13, v13, v14
	ds_write_b32 v15, v13
